# QKV phase prologue: the three units' table loads issued together, one wait instead of three serial load-wait rounds
# speedup vs baseline: 1.0037x; 1.0037x over previous
.LBB0_85:
	s_and_b32 s3, s6, 1
	s_cmp_eq_u32 s3, 0
	s_cselect_b64 s[8:9], -1, 0
	s_cmp_eq_u32 s3, 1
	s_cselect_b64 s[4:5], -1, 0
	v_writelane_b32 v255, s4, 24
	v_mbcnt_lo_u32_b32 v0, -1, 0
	v_mbcnt_hi_u32_b32 v0, -1, v0
	s_mul_i32 s18, s6, 0x600000
	v_add_u32_e32 v0, s95, v0
	v_writelane_b32 v255, s5, 25
	v_writelane_b32 v255, s8, 26
	s_mov_b32 s4, s6
	s_and_b64 vcc, exec, s[8:9]
	v_writelane_b32 v255, s9, 27
	v_writelane_b32 v255, s4, 28
	s_nop 1
	v_writelane_b32 v255, s5, 29
	s_mov_b64 s[4:5], -1
	s_cbranch_vccnz .LBB0_152
	v_readlane_b32 s36, v251, 0
	v_readlane_b32 s4, v255, 28
	v_readlane_b32 s40, v251, 4
	v_readlane_b32 s41, v251, 5
	s_lshr_b32 s3, s4, 1
	v_readlane_b32 s42, v251, 6
	v_readlane_b32 s43, v251, 7
	v_readlane_b32 s44, v251, 8
	v_readlane_b32 s45, v251, 9
	v_readlane_b32 s46, v251, 10
	v_readlane_b32 s47, v251, 11
	v_readlane_b32 s48, v251, 12
	v_readlane_b32 s49, v251, 13
	s_mov_b64 s[8:9], s[40:41]
	s_mul_i32 s4, s3, 0x3000
	s_mov_b64 s[16:17], s[48:49]
	v_readlane_b32 s5, v255, 29
	s_add_u32 s6, s16, s4
	s_mul_i32 s0, s3, 0xc00
	s_addc_u32 s7, s17, 0
	s_lshl_b64 s[4:5], s[0:1], 2
	v_readlane_b32 s3, v251, 48
	s_add_u32 s8, s3, s4
	v_readlane_b32 s3, v251, 49
	s_addc_u32 s9, s3, s5
	s_movk_i32 s3, 0xff
	s_mov_b64 s[10:11], s[42:43]
	v_cmp_lt_i32_e64 s[4:5], s3, v0
	v_readlane_b32 s37, v251, 1
	v_readlane_b32 s38, v251, 2
	v_readlane_b32 s39, v251, 3
	v_readlane_b32 s50, v251, 14
	v_readlane_b32 s51, v251, 15
	s_mov_b64 s[12:13], s[44:45]
	s_mov_b64 s[14:15], s[46:47]
	s_and_saveexec_b64 s[10:11], s[4:5]
	s_xor_b64 s[10:11], exec, s[10:11]
	s_cbranch_execz .Lmy_p1_b
	v_readlane_b32 s20, v251, 32
	v_readlane_b32 s21, v251, 33
	v_readlane_b32 s22, v251, 34
	v_readlane_b32 s23, v251, 35
	v_readlane_b32 s24, v251, 36
	v_readlane_b32 s25, v251, 37
	v_readlane_b32 s26, v251, 38
	v_readlane_b32 s27, v251, 39
	v_readlane_b32 s3, v251, 52
	s_nop 1
	v_add_u32_e32 v230, s3, v0
	v_readlane_b32 s3, v251, 54
	v_lshl_add_u64 v[12:13], v[230:231], 2, s[26:27]
	s_nop 0
	v_add_u32_e32 v230, s3, v0
	v_readlane_b32 s3, v251, 56
	v_lshl_add_u64 v[14:15], v[230:231], 2, s[26:27]
	s_nop 0
	v_add_u32_e32 v230, s3, v0
	v_add_co_u32_e32 v12, vcc, 0x47ff000, v12
	v_lshl_add_u64 v[2:3], v[230:231], 2, s[26:27]
	s_nop 0
	v_addc_co_u32_e32 v13, vcc, 0, v13, vcc
	global_load_dword v12, v[12:13], off offset:3072
	v_add_co_u32_e32 v14, vcc, 0x47ff000, v14
	s_nop 1
	v_addc_co_u32_e32 v15, vcc, 0, v15, vcc
	global_load_dword v14, v[14:15], off offset:3072
	v_add_co_u32_e32 v2, vcc, 0x47ff000, v2
	s_nop 1
	v_addc_co_u32_e32 v3, vcc, 0, v3, vcc
	global_load_dword v2, v[2:3], off offset:3072
.Lmy_p1_b:
	s_or_saveexec_b64 s[10:11], s[10:11]
	v_lshl_add_u32 v1, v0, 2, 0
	s_xor_b64 exec, exec, s[10:11]
	s_cbranch_execz .Lmy_p1_j
	v_readlane_b32 s3, v251, 53
	s_nop 1
	v_add_u32_e32 v2, s3, v0
	v_readlane_b32 s3, v251, 55
	v_ashrrev_i32_e32 v3, 31, v2
	v_lshlrev_b64 v[4:5], 2, v[2:3]
	v_add_u32_e32 v8, s3, v0
	v_readlane_b32 s3, v251, 57
	v_ashrrev_i32_e32 v9, 31, v8
	v_lshlrev_b64 v[10:11], 2, v[8:9]
	v_add_u32_e32 v22, s3, v0
	v_ashrrev_i32_e32 v23, 31, v22
	v_lshlrev_b64 v[16:17], 2, v[22:23]
	v_lshl_add_u64 v[6:7], s[8:9], 0, v[4:5]
	global_load_dword v3, v[6:7], off
	v_lshl_add_u64 v[4:5], s[6:7], 0, v[4:5]
	global_load_dword v4, v[4:5], off
	v_lshl_add_u64 v[18:19], s[8:9], 0, v[10:11]
	global_load_dword v9, v[18:19], off
	v_lshl_add_u64 v[10:11], s[6:7], 0, v[10:11]
	global_load_dword v10, v[10:11], off
	v_lshl_add_u64 v[20:21], s[8:9], 0, v[16:17]
	global_load_dword v15, v[20:21], off
	v_lshl_add_u64 v[16:17], s[6:7], 0, v[16:17]
	global_load_dword v16, v[16:17], off
	s_movk_i32 s3, 0x7ff
	v_add_u32_e32 v2, 0x3ff, v2
	v_add_u32_e32 v8, 0x3ff, v8
	v_add_u32_e32 v22, 0x3ff, v22
	v_cmp_gt_u32_e32 vcc, s3, v2
	v_add_u32_e32 v5, 0x20340, v1
	v_cndmask_b32_e32 v2, 1.0, v213, vcc
	v_cmp_gt_u32_e32 vcc, s3, v8
	v_add_u32_e32 v11, 0x20f40, v1
	v_cndmask_b32_e32 v8, 1.0, v213, vcc
	v_cmp_gt_u32_e32 vcc, s3, v22
	v_add_u32_e32 v1, 0x21b40, v1
	v_cndmask_b32_e32 v22, 1.0, v213, vcc
	v_mul_f32_e32 v6, 0x3c010204, v2
	v_mul_f32_e32 v7, 0x3c010204, v8
	v_mul_f32_e32 v17, 0x3c010204, v22
	s_waitcnt vmcnt(5)
	v_max_f32_e32 v3, v3, v3
	v_max_f32_e32 v3, 0xda24260, v3
	v_mul_f32_e32 v3, v6, v3
	ds_write_b32 v5, v3
	s_waitcnt vmcnt(4)
	v_mul_f32_e32 v12, v2, v4
	s_waitcnt vmcnt(3)
	v_max_f32_e32 v9, v9, v9
	v_max_f32_e32 v9, 0xda24260, v9
	v_mul_f32_e32 v9, v7, v9
	ds_write_b32 v11, v9
	s_waitcnt vmcnt(2)
	v_mul_f32_e32 v14, v8, v10
	s_waitcnt vmcnt(1)
	v_max_f32_e32 v15, v15, v15
	v_max_f32_e32 v15, 0xda24260, v15
	v_mul_f32_e32 v15, v17, v15
	ds_write_b32 v1, v15
	s_waitcnt vmcnt(0)
	v_mul_f32_e32 v2, v22, v16
.Lmy_p1_j:
	s_or_b64 exec, exec, s[10:11]
	s_add_i32 s3, 0, 0x20340
	v_lshl_add_u32 v3, v0, 2, s3
	s_add_i32 s3, 0, 0x20f40
	v_lshl_add_u32 v4, v0, 2, s3
	s_waitcnt vmcnt(0)
	ds_write_b32 v3, v12 offset:1024
	ds_write_b32 v4, v14 offset:1024
